# v35 + the remaining attention-epilogue cross-half sums (softmax denominators, head-norm sum of squares) via v_permlane32_swap instead of ds_bpermute
# speedup vs baseline: 1.0052x; 1.0052x over previous
; __device__ __forceinline__ void attn_unit(int b, int h, int qb, bf16_t* Q, const bf16_t* __restrict__ K, const bf16_t* __restrict__ Vt, const bf16_t* __restrict__ Z, const float* __restrict__ hg, float lam, ...
;     ...
;     const float l1 = lsum[0] + __shfl_xor(lsum[0], 32), l2 = lsum[1] + __shfl_xor(lsum[1], 32);
;     const float i1 = 1.f / l1, i2 = lam / l2;
;     float ss = 0.f;
; #pragma unroll
;     for (int d = 0; d < 4; ++d)
; #pragma unroll
;         for (int r = 0; r < 16; ++r) { const float v = o[0][d][r] * i1 - o[1][d][r] * i2; o[0][d][r] = v; ss += v * v; }
.LBB0_236:
	v_ashrrev_i32_e32 v138, 5, v230
	v_and_or_b32 v140, v230, 31, s82
	v_mov_b32_e32 v141, s83
	v_lshlrev_b64 v[140:141], 11, v[140:141]
	v_lshl_add_u64 v[140:141], v[140:141], 0, s[18:19]
	v_lshlrev_b32_e32 v138, 3, v138
	v_lshlrev_b64 v[140:141], 1, v[140:141]
	v_ashrrev_i32_e32 v139, 31, v138
	v_lshl_add_u64 v[140:141], s[28:29], 0, v[140:141]
	v_lshlrev_b64 v[138:139], 1, v[138:139]
	v_lshl_add_u64 v[140:141], v[140:141], 0, v[138:139]
	global_load_dwordx4 v[146:149], v[140:141], off
	global_load_dwordx4 v[150:153], v[140:141], off offset:32
	global_load_dwordx4 v[154:157], v[140:141], off offset:64
	global_load_dwordx4 v[158:161], v[140:141], off offset:96
	global_load_dwordx4 v[162:165], v[140:141], off offset:128
	global_load_dwordx4 v[166:169], v[140:141], off offset:160
	global_load_dwordx4 v[170:173], v[140:141], off offset:192
	global_load_dwordx4 v[174:177], v[140:141], off offset:224
	v_mov_b32_e32 v128, v224
	v_mov_b32_e32 v129, v225
	s_nop 1
	v_permlane32_swap_b32_e32 v128, v224
	v_permlane32_swap_b32_e32 v129, v225
	v_pk_add_f32 v[128:129], v[224:225], v[128:129]
	s_nop 0
	v_div_scale_f32 v130, s[8:9], v129, v129, s71
	v_rcp_f32_e32 v132, v130
	v_div_scale_f32 v131, vcc, s71, v129, s71
	v_div_scale_f32 v133, s[8:9], v128, v128, 1.0
	v_fma_f32 v135, -v130, v132, 1.0
	v_fmac_f32_e32 v132, v135, v132
	v_mul_f32_e32 v135, v131, v132
	v_rcp_f32_e32 v134, v133
	v_fma_f32 v136, -v130, v135, v131
	v_fmac_f32_e32 v135, v136, v132
	v_fma_f32 v130, -v130, v135, v131
	v_div_fmas_f32 v130, v130, v132, v135
	v_div_fixup_f32 v129, v130, v129, s71
	v_fma_f32 v130, -v133, v134, 1.0
	v_fmac_f32_e32 v134, v130, v134
	v_div_scale_f32 v130, vcc, 1.0, v128, 1.0
	v_mul_f32_e32 v131, v130, v134
	v_fma_f32 v132, -v133, v131, v130
	v_fmac_f32_e32 v131, v132, v134
	v_fma_f32 v130, -v133, v131, v130
	v_div_fmas_f32 v130, v130, v134, v131
	v_div_fixup_f32 v128, v130, v128, 1.0
	v_mov_b32_e32 v131, v112
	v_mov_b32_e32 v112, v65
	v_mov_b32_e32 v130, v64
	v_pk_mul_f32 v[64:65], v[112:113], v[128:129]
	v_pk_mul_f32 v[130:131], v[130:131], v[128:129]
	v_sub_f32_e32 v132, v64, v65
	v_mov_b32_e32 v64, v66
	v_mov_b32_e32 v65, v114
	v_pk_mul_f32 v[64:65], v[64:65], v[128:129]
	v_mov_b32_e32 v114, v67
	v_sub_f32_e32 v133, v64, v65
	v_pk_mul_f32 v[64:65], v[114:115], v[128:129]
	v_sub_f32_e32 v131, v130, v131
	v_sub_f32_e32 v134, v64, v65
	v_mov_b32_e32 v64, v68
	v_mov_b32_e32 v65, v116
	v_pk_mul_f32 v[64:65], v[64:65], v[128:129]
	v_mov_b32_e32 v116, v69
	v_sub_f32_e32 v135, v64, v65
	v_pk_mul_f32 v[64:65], v[116:117], v[128:129]
	s_nop 0
	v_sub_f32_e32 v136, v64, v65
	v_mov_b32_e32 v64, v70
	v_mov_b32_e32 v65, v118
	v_pk_mul_f32 v[64:65], v[64:65], v[128:129]
	v_mov_b32_e32 v118, v71
	v_sub_f32_e32 v130, v64, v65
	v_pk_mul_f32 v[64:65], v[118:119], v[128:129]
	s_nop 0
	v_sub_f32_e32 v119, v64, v65
	v_mov_b32_e32 v64, v72
	v_mov_b32_e32 v65, v120
	v_pk_mul_f32 v[64:65], v[64:65], v[128:129]
	v_mov_b32_e32 v120, v73
	v_sub_f32_e32 v118, v64, v65
	v_pk_mul_f32 v[64:65], v[120:121], v[128:129]
	s_nop 0
	v_sub_f32_e32 v117, v64, v65
	v_mov_b32_e32 v64, v74
	v_mov_b32_e32 v65, v122
	v_pk_mul_f32 v[64:65], v[64:65], v[128:129]
	v_mov_b32_e32 v122, v75
	v_sub_f32_e32 v116, v64, v65
	v_pk_mul_f32 v[64:65], v[122:123], v[128:129]
	s_nop 0
	v_sub_f32_e32 v115, v64, v65
	v_mov_b32_e32 v64, v76
	v_mov_b32_e32 v65, v124
	v_pk_mul_f32 v[64:65], v[64:65], v[128:129]
	v_mov_b32_e32 v124, v77
	v_sub_f32_e32 v114, v64, v65
	v_pk_mul_f32 v[64:65], v[124:125], v[128:129]
	s_nop 0
	v_sub_f32_e32 v113, v64, v65
	v_mov_b32_e32 v64, v78
	v_mov_b32_e32 v65, v126
	v_pk_mul_f32 v[64:65], v[64:65], v[128:129]
	v_mov_b32_e32 v126, v79
	v_sub_f32_e32 v112, v64, v65
	v_pk_mul_f32 v[64:65], v[126:127], v[128:129]
	s_nop 0
	v_sub_f32_e32 v78, v64, v65
	v_mov_b32_e32 v65, v96
	v_mov_b32_e32 v96, v49
	v_mov_b32_e32 v64, v48
	v_pk_mul_f32 v[48:49], v[96:97], v[128:129]
	v_pk_mul_f32 v[64:65], v[64:65], v[128:129]
	v_sub_f32_e32 v76, v48, v49
	v_mov_b32_e32 v48, v50
	v_mov_b32_e32 v49, v98
	v_pk_mul_f32 v[48:49], v[48:49], v[128:129]
	v_mov_b32_e32 v98, v51
	v_sub_f32_e32 v75, v48, v49
	v_pk_mul_f32 v[48:49], v[98:99], v[128:129]
	v_sub_f32_e32 v77, v64, v65
	v_sub_f32_e32 v74, v48, v49
	v_mov_b32_e32 v48, v52
	v_mov_b32_e32 v49, v100
	v_pk_mul_f32 v[48:49], v[48:49], v[128:129]
	v_mov_b32_e32 v100, v53
	v_sub_f32_e32 v73, v48, v49
	v_pk_mul_f32 v[48:49], v[100:101], v[128:129]
	s_nop 0
	v_sub_f32_e32 v72, v48, v49
	v_mov_b32_e32 v48, v54
	v_mov_b32_e32 v49, v102
	v_pk_mul_f32 v[48:49], v[48:49], v[128:129]
	v_mov_b32_e32 v102, v55
	v_sub_f32_e32 v71, v48, v49
	v_pk_mul_f32 v[48:49], v[102:103], v[128:129]
	s_nop 0
	v_sub_f32_e32 v70, v48, v49
	v_mov_b32_e32 v48, v56
	v_mov_b32_e32 v49, v104
	v_pk_mul_f32 v[48:49], v[48:49], v[128:129]
	v_mov_b32_e32 v104, v57
	v_sub_f32_e32 v69, v48, v49
	v_pk_mul_f32 v[48:49], v[104:105], v[128:129]
	s_nop 0
	v_sub_f32_e32 v68, v48, v49
	v_mov_b32_e32 v48, v58
	v_mov_b32_e32 v49, v106
	v_pk_mul_f32 v[48:49], v[48:49], v[128:129]
	v_mov_b32_e32 v106, v59
	v_sub_f32_e32 v67, v48, v49
	v_pk_mul_f32 v[48:49], v[106:107], v[128:129]
	s_nop 0
	v_sub_f32_e32 v66, v48, v49
	v_mov_b32_e32 v48, v60
	v_mov_b32_e32 v49, v108
	v_pk_mul_f32 v[48:49], v[48:49], v[128:129]
	v_mov_b32_e32 v108, v61
	v_sub_f32_e32 v65, v48, v49
	v_pk_mul_f32 v[48:49], v[108:109], v[128:129]
	s_nop 0
	v_sub_f32_e32 v64, v48, v49
	v_mov_b32_e32 v48, v62
	v_mov_b32_e32 v49, v110
	v_pk_mul_f32 v[48:49], v[48:49], v[128:129]
	v_mov_b32_e32 v110, v63
	v_sub_f32_e32 v61, v48, v49
	v_pk_mul_f32 v[48:49], v[110:111], v[128:129]
	s_nop 0
	v_sub_f32_e32 v60, v48, v49
	v_mov_b32_e32 v49, v80
; __device__ __forceinline__ void attn_unit(int b, int h, int qb, bf16_t* Q, const bf16_t* __restrict__ K, const bf16_t* __restrict__ Vt, const bf16_t* __restrict__ Z, const float* __restrict__ hg, float lam, ...
;     ...
;     for (int d = 0; d < 4; ++d)
; #pragma unroll
;         for (int r = 0; r < 16; ++r) { const float v = o[0][d][r] * i1 - o[1][d][r] * i2; o[0][d][r] = v; ss += v * v; }
;     ss += __shfl_xor(ss, 32);
	v_mov_b32_e32 v80, v17
	v_mov_b32_e32 v48, v16
	v_pk_mul_f32 v[16:17], v[80:81], v[128:129]
	v_pk_mul_f32 v[48:49], v[48:49], v[128:129]
	v_sub_f32_e32 v58, v16, v17
	v_mov_b32_e32 v16, v18
	v_mov_b32_e32 v17, v82
	v_pk_mul_f32 v[16:17], v[16:17], v[128:129]
	v_mov_b32_e32 v82, v19
	v_sub_f32_e32 v57, v16, v17
	v_pk_mul_f32 v[16:17], v[82:83], v[128:129]
	v_sub_f32_e32 v59, v48, v49
	v_sub_f32_e32 v56, v16, v17
	v_mov_b32_e32 v16, v20
	v_mov_b32_e32 v17, v84
	v_pk_mul_f32 v[16:17], v[16:17], v[128:129]
	v_mov_b32_e32 v84, v21
	v_sub_f32_e32 v55, v16, v17
	v_pk_mul_f32 v[16:17], v[84:85], v[128:129]
	s_nop 0
	v_sub_f32_e32 v54, v16, v17
	v_mov_b32_e32 v16, v22
	v_mov_b32_e32 v17, v86
	v_pk_mul_f32 v[16:17], v[16:17], v[128:129]
	v_mov_b32_e32 v86, v23
	v_sub_f32_e32 v53, v16, v17
	v_pk_mul_f32 v[16:17], v[86:87], v[128:129]
	s_nop 0
	v_sub_f32_e32 v52, v16, v17
	v_mov_b32_e32 v16, v24
	v_mov_b32_e32 v17, v88
	v_pk_mul_f32 v[16:17], v[16:17], v[128:129]
	v_mov_b32_e32 v88, v25
	v_sub_f32_e32 v51, v16, v17
	v_pk_mul_f32 v[16:17], v[88:89], v[128:129]
	s_nop 0
	v_sub_f32_e32 v50, v16, v17
	v_mov_b32_e32 v16, v26
	v_mov_b32_e32 v17, v90
	v_pk_mul_f32 v[16:17], v[16:17], v[128:129]
	v_mov_b32_e32 v90, v27
	v_sub_f32_e32 v49, v16, v17
	v_pk_mul_f32 v[16:17], v[90:91], v[128:129]
	s_nop 0
	v_sub_f32_e32 v48, v16, v17
	v_mov_b32_e32 v16, v28
	v_mov_b32_e32 v17, v92
	v_pk_mul_f32 v[16:17], v[16:17], v[128:129]
	v_mov_b32_e32 v92, v29
	v_sub_f32_e32 v27, v16, v17
	v_pk_mul_f32 v[16:17], v[92:93], v[128:129]
	s_nop 0
	v_sub_f32_e32 v26, v16, v17
	v_mov_b32_e32 v16, v30
	v_mul_f32_e32 v30, v131, v131
	v_fmac_f32_e32 v30, v132, v132
	v_fmac_f32_e32 v30, v133, v133
	v_fmac_f32_e32 v30, v134, v134
	v_fmac_f32_e32 v30, v135, v135
	v_fmac_f32_e32 v30, v136, v136
	v_fmac_f32_e32 v30, v130, v130
	v_fmac_f32_e32 v30, v119, v119
	v_fmac_f32_e32 v30, v118, v118
	v_fmac_f32_e32 v30, v117, v117
	v_fmac_f32_e32 v30, v116, v116
	v_fmac_f32_e32 v30, v115, v115
	v_fmac_f32_e32 v30, v114, v114
	v_fmac_f32_e32 v30, v113, v113
	v_fmac_f32_e32 v30, v112, v112
	v_fmac_f32_e32 v30, v78, v78
	v_fmac_f32_e32 v30, v77, v77
	v_fmac_f32_e32 v30, v76, v76
	v_fmac_f32_e32 v30, v75, v75
	v_fmac_f32_e32 v30, v74, v74
	v_fmac_f32_e32 v30, v73, v73
	v_fmac_f32_e32 v30, v72, v72
	v_fmac_f32_e32 v30, v71, v71
	v_fmac_f32_e32 v30, v70, v70
	v_fmac_f32_e32 v30, v69, v69
	v_fmac_f32_e32 v30, v68, v68
	v_fmac_f32_e32 v30, v67, v67
	v_fmac_f32_e32 v30, v66, v66
	v_fmac_f32_e32 v30, v65, v65
	v_fmac_f32_e32 v30, v64, v64
	v_fmac_f32_e32 v30, v61, v61
	v_fmac_f32_e32 v30, v60, v60
	v_fmac_f32_e32 v30, v59, v59
	v_fmac_f32_e32 v30, v58, v58
	v_fmac_f32_e32 v30, v57, v57
	v_fmac_f32_e32 v30, v56, v56
	v_mov_b32_e32 v17, v94
	v_fmac_f32_e32 v30, v55, v55
	v_pk_mul_f32 v[16:17], v[16:17], v[128:129]
	v_mov_b32_e32 v94, v31
	v_fmac_f32_e32 v30, v54, v54
	v_sub_f32_e32 v25, v16, v17
	v_pk_mul_f32 v[16:17], v[94:95], v[128:129]
	v_fmac_f32_e32 v30, v53, v53
	v_sub_f32_e32 v24, v16, v17
	v_mov_b32_e32 v17, v32
	v_mov_b32_e32 v32, v1
	v_fmac_f32_e32 v30, v52, v52
	v_mov_b32_e32 v16, v0
	v_pk_mul_f32 v[0:1], v[32:33], v[128:129]
	v_fmac_f32_e32 v30, v51, v51
	v_sub_f32_e32 v22, v0, v1
	v_mov_b32_e32 v0, v2
	v_mov_b32_e32 v1, v34
	v_fmac_f32_e32 v30, v50, v50
	v_pk_mul_f32 v[0:1], v[0:1], v[128:129]
	v_mov_b32_e32 v34, v3
	v_fmac_f32_e32 v30, v49, v49
	v_sub_f32_e32 v21, v0, v1
	v_pk_mul_f32 v[0:1], v[34:35], v[128:129]
	v_fmac_f32_e32 v30, v48, v48
	v_sub_f32_e32 v20, v0, v1
	v_mov_b32_e32 v0, v4
	v_mov_b32_e32 v1, v36
	v_fmac_f32_e32 v30, v27, v27
	v_pk_mul_f32 v[0:1], v[0:1], v[128:129]
	v_mov_b32_e32 v36, v5
	v_fmac_f32_e32 v30, v26, v26
	v_pk_mul_f32 v[16:17], v[16:17], v[128:129]
	v_sub_f32_e32 v19, v0, v1
	v_pk_mul_f32 v[0:1], v[36:37], v[128:129]
	v_fmac_f32_e32 v30, v25, v25
	v_sub_f32_e32 v23, v16, v17
	v_sub_f32_e32 v18, v0, v1
	v_mov_b32_e32 v0, v6
	v_mov_b32_e32 v1, v38
	v_mov_b32_e32 v38, v7
	v_fmac_f32_e32 v30, v24, v24
	v_pk_mul_f32 v[0:1], v[0:1], v[128:129]
	v_pk_mul_f32 v[2:3], v[38:39], v[128:129]
	v_fmac_f32_e32 v30, v23, v23
	v_mov_b32_e32 v4, v2
	v_mov_b32_e32 v5, v0
	v_mov_b32_e32 v0, v3
	v_fmac_f32_e32 v30, v22, v22
	v_pk_add_f32 v[16:17], v[4:5], v[0:1] neg_lo:[0,1] neg_hi:[0,1]
	v_mov_b32_e32 v0, v8
	v_mov_b32_e32 v1, v40
	v_mov_b32_e32 v40, v9
	v_fmac_f32_e32 v30, v21, v21
	v_pk_mul_f32 v[0:1], v[0:1], v[128:129]
	v_pk_mul_f32 v[2:3], v[40:41], v[128:129]
	v_fmac_f32_e32 v30, v20, v20
	v_mov_b32_e32 v4, v2
	v_mov_b32_e32 v5, v0
	v_mov_b32_e32 v0, v3
	v_fmac_f32_e32 v30, v19, v19
	v_pk_mul_f32 v[28:29], v[16:17], v[16:17]
	v_pk_add_f32 v[6:7], v[4:5], v[0:1] neg_lo:[0,1] neg_hi:[0,1]
	v_mov_b32_e32 v0, v10
	v_mov_b32_e32 v1, v42
	v_mov_b32_e32 v42, v11
	v_fmac_f32_e32 v30, v18, v18
	v_pk_mul_f32 v[0:1], v[0:1], v[128:129]
	v_pk_mul_f32 v[2:3], v[42:43], v[128:129]
	v_add_f32_e32 v29, v29, v30
	v_pk_mul_f32 v[8:9], v[6:7], v[6:7]
	v_mov_b32_e32 v4, v2
	v_mov_b32_e32 v5, v0
	v_mov_b32_e32 v0, v3
	v_add_f32_e32 v28, v28, v29
	v_pk_add_f32 v[4:5], v[4:5], v[0:1] neg_lo:[0,1] neg_hi:[0,1]
	v_mov_b32_e32 v0, v129
	v_add_f32_e32 v9, v9, v28
	v_pk_mul_f32 v[10:11], v[4:5], v[4:5]
	v_pk_mul_f32 v[2:3], v[44:45], v[0:1] op_sel_hi:[1,0]
	v_add_f32_e32 v8, v8, v9
	v_pk_fma_f32 v[2:3], v[12:13], v[128:129], v[2:3] op_sel_hi:[1,0,1] neg_lo:[0,0,1] neg_hi:[0,0,1]
	v_add_f32_e32 v8, v11, v8
	v_pk_mul_f32 v[12:13], v[2:3], v[2:3]
	v_pk_mul_f32 v[0:1], v[46:47], v[0:1] op_sel_hi:[1,0]
	v_add_f32_e32 v8, v10, v8
	v_pk_fma_f32 v[0:1], v[14:15], v[128:129], v[0:1] op_sel_hi:[1,0,1] neg_lo:[0,0,1] neg_hi:[0,0,1]
	v_add_f32_e32 v8, v12, v8
	v_pk_mul_f32 v[14:15], v[0:1], v[0:1]
	v_add_f32_e32 v8, v13, v8
	v_add_f32_e32 v8, v14, v8
	v_add_f32_e32 v8, v15, v8
	v_mov_b32_e32 v9, v8
	s_nop 1
	v_permlane32_swap_b32_e32 v9, v8
	v_mov_b32_e32 v15, v230
	s_waitcnt lgkmcnt(0)
; __device__ __forceinline__ unsigned pk2(float lo, float hi) { return pg8::cvt_pk_bf16(lo, hi); }
; __device__ __forceinline__ float siluf_(float v) { return v * __builtin_amdgcn_rcpf(1.f + __builtin_amdgcn_exp2f(-LOG2E * v)); }
; __device__ __forceinline__ void attn_unit(int b, int h, int qb, bf16_t* Q, const bf16_t* __restrict__ K, const bf16_t* __restrict__ Vt, const bf16_t* __restrict__ Z, const float* __restrict__ hg, float lam, ...
;     ...
;     const float rs = rsqrtf(ss * (1.f / 128.f) + EPS) * (1.f - LAM0);
;     int lane_l = lane; asm volatile("" : "+v"(lane_l));
;     const size_t off = (rowbase + qw0 + (lane_l & 31)) * BR + h * 128 + 4 * (lane_l >> 5);
;     __builtin_amdgcn_sched_barrier(0);
;     const int hi_l = lane_l >> 5;
;     const size_t offw = off - 4 * hi_l;
; #pragma unroll
;     for (int d = 0; d < 4; ++d)
; #pragma unroll
;         for (int ip = 0; ip < 2; ++ip) { __builtin_amdgcn_sched_barrier(0);
;             u32x2 w[2];
;             const u32x4 zl = *(const u32x4*)(Z + offw + 32 * d + 16 * ip + 8 * hi_l);
;             const unsigned zsx = hi_l ? zl.x : zl.z, zsy = hi_l ? zl.y : zl.w;
;             const unsigned zrx = __shfl_xor(zsx, 32), zry = __shfl_xor(zsy, 32);
; #pragma unroll
;             for (int k = 0; k < 2; ++k) { const int i = 2 * ip + k, e = 32 * d + 8 * i;
;                 const f32x4 g4 = *(const f32x4*)(hg + e + 4 * hi_l);
;                 const u32x2 z2 = (k == 0) ? (hi_l ? (u32x2){zrx, zry} : (u32x2){zl.x, zl.y}) : (hi_l ? (u32x2){zl.z, zl.w} : (u32x2){zrx, zry});
;                 const float v0 = o[0][d][4 * i] * rs * g4[0] * siluf_(bflo(z2.x)), v1 = o[0][d][4 * i + 1] * rs * g4[1] * siluf_(bfhi(z2.x));
;                 const float v2 = o[0][d][4 * i + 2] * rs * g4[2] * siluf_(bflo(z2.y)), v3 = o[0][d][4 * i + 3] * rs * g4[3] * siluf_(bfhi(z2.y));
;                 w[k] = (u32x2){pk2(v0, v1), pk2(v2, v3)}; }
;             const u32x2 snd = hi_l ? w[0] : w[1];
;             const unsigned rx = __shfl_xor(snd.x, 32), ry = __shfl_xor(snd.y, 32);
;             const u32x4 st = hi_l ? (u32x4){rx, ry, w[1].x, w[1].y} : (u32x4){w[0].x, w[0].y, rx, ry};
;             *(u32x4*)(Q + offw + 32 * d + 16 * ip + 8 * hi_l) = st; }
	v_add_f32_e32 v8, v8, v9
	v_fmamk_f32 v8, v8, 0x3c000000, v245
	v_mul_f32_e32 v9, 0x4b800000, v8
	v_cmp_gt_f32_e32 vcc, s81, v8
	v_ashrrev_i32_e32 v28, 5, v15
	v_lshlrev_b32_e32 v137, 4, v28
	v_add_u32_e32 v137, 0x11100, v137
	v_lshlrev_b32_e32 v10, 2, v28
	v_cndmask_b32_e32 v8, v8, v9, vcc
	v_rsq_f32_e32 v8, v8
	v_ashrrev_i32_e32 v11, 31, v10
	v_mul_f32_e32 v9, 0x45800000, v8
	v_cndmask_b32_e32 v8, v8, v9, vcc
	v_mul_f32_e32 v14, 0x3f4ccccd, v8
	v_and_or_b32 v8, v15, 31, s82
	v_mov_b32_e32 v9, s83
	v_lshlrev_b64 v[8:9], 11, v[8:9]
	v_lshl_add_u64 v[8:9], v[8:9], 0, s[18:19]
	v_lshlrev_b32_e32 v28, 3, v28
	v_lshlrev_b64 v[8:9], 1, v[8:9]
	v_ashrrev_i32_e32 v29, 31, v28
	v_lshl_add_u64 v[12:13], s[28:29], 0, v[8:9]
	v_lshlrev_b64 v[28:29], 1, v[28:29]
	v_lshl_add_u64 v[8:9], s[34:35], 0, v[8:9]
	v_lshl_add_u64 v[12:13], v[12:13], 0, v[28:29]
	v_cmp_gt_u32_e32 vcc, 32, v15
	v_lshl_add_u64 v[10:11], v[10:11], 2, s[54:55]
	v_lshl_add_u64 v[8:9], v[8:9], 0, v[28:29]
	ds_read_b128 v[32:35], v137
	v_mul_f32_e32 v37, v131, v14
	v_mul_f32_e32 v39, v132, v14
	v_mul_f32_e32 v41, v133, v14
	v_mul_f32_e32 v43, v134, v14
	s_waitcnt vmcnt(7)
	v_mov_b32_e32 v28, v146
	v_mov_b32_e32 v29, v147
	v_mov_b32_e32 v30, v148
	v_mov_b32_e32 v31, v149
	s_nop 1
	v_permlane32_swap_b32_e32 v28, v30
	v_permlane32_swap_b32_e32 v29, v31
	s_waitcnt lgkmcnt(0)
	v_mov_b32_e32 v45, v32
	v_mov_b32_e32 v47, v34
	v_lshlrev_b32_e32 v36, 16, v28
	v_and_b32_e32 v38, 0xffff0000, v28
	v_lshlrev_b32_e32 v40, 16, v29
	v_and_b32_e32 v42, 0xffff0000, v29
	v_mul_f32_e32 v28, 0xbfb8aa3b, v36
	v_mul_f32_e32 v29, 0xbfb8aa3b, v38
	v_mul_f32_e32 v32, 0xbfb8aa3b, v40
	v_mul_f32_e32 v34, 0xbfb8aa3b, v42
	v_exp_f32_e32 v28, v28
	v_exp_f32_e32 v29, v29
	v_exp_f32_e32 v32, v32
	v_exp_f32_e32 v34, v34
	v_add_f32_e32 v28, 1.0, v28
	v_add_f32_e32 v29, 1.0, v29
	v_add_f32_e32 v46, 1.0, v32
	v_add_f32_e32 v34, 1.0, v34
	v_rcp_f32_e32 v44, v28
	v_rcp_f32_e32 v32, v29
	v_rcp_f32_e32 v46, v46
	v_rcp_f32_e32 v34, v34
	v_pk_mul_f32 v[28:29], v[44:45], v[36:37]
	v_pk_mul_f32 v[32:33], v[32:33], v[38:39]
	v_pk_mul_f32 v[36:37], v[46:47], v[40:41]
	v_pk_mul_f32 v[34:35], v[34:35], v[42:43]
	v_mul_f32_e32 v28, v28, v29
	v_mul_f32_e32 v29, v32, v33
	v_mul_f32_e32 v32, v36, v37
	v_mul_f32_e32 v33, v34, v35
	v_cvt_pk_bf16_f32 v44, v28, v29
	v_cvt_pk_bf16_f32 v45, v32, v33
	ds_read_b128 v[32:35], v137 offset:32
	v_mov_b32_e32 v15, v30
	v_lshlrev_b32_e32 v28, 16, v15
	v_lshlrev_b32_e32 v38, 16, v31
	v_and_b32_e32 v36, 0xffff0000, v15
	v_and_b32_e32 v40, 0xffff0000, v31
	v_mul_f32_e32 v15, 0xbfb8aa3b, v28
	v_mul_f32_e32 v31, 0xbfb8aa3b, v38
	v_mul_f32_e32 v30, 0xbfb8aa3b, v36
	v_mul_f32_e32 v42, 0xbfb8aa3b, v40
	v_exp_f32_e32 v15, v15
	v_exp_f32_e32 v31, v31
	v_exp_f32_e32 v30, v30
	v_exp_f32_e32 v42, v42
	v_add_f32_e32 v15, 1.0, v15
	v_add_f32_e32 v31, 1.0, v31
	v_add_f32_e32 v43, 1.0, v30
	v_add_f32_e32 v46, 1.0, v42
	v_rcp_f32_e32 v30, v15
	v_rcp_f32_e32 v42, v31
	v_mul_f32_e32 v29, v135, v14
	v_mul_f32_e32 v39, v130, v14
	v_mul_f32_e32 v37, v136, v14
	v_mul_f32_e32 v41, v119, v14
	s_waitcnt lgkmcnt(0)
	v_mov_b32_e32 v31, v32
	v_rcp_f32_e32 v32, v43
	v_mov_b32_e32 v43, v34
	v_rcp_f32_e32 v34, v46
	v_pk_mul_f32 v[28:29], v[30:31], v[28:29]
	v_pk_mul_f32 v[30:31], v[42:43], v[38:39]
	v_mul_f32_e32 v15, v28, v29
	v_mul_f32_e32 v38, v30, v31
	v_pk_mul_f32 v[28:29], v[32:33], v[36:37]
	v_pk_mul_f32 v[30:31], v[34:35], v[40:41]
	v_mul_f32_e32 v28, v28, v29
	v_mul_f32_e32 v29, v30, v31
	v_cvt_pk_bf16_f32 v15, v15, v28
	v_cvt_pk_bf16_f32 v29, v38, v29
	s_nop 0
	v_mov_b32_e32 v31, v29
	v_mov_b32_e32 v30, v15
	v_mov_b32_e32 v28, v44
	v_mov_b32_e32 v29, v45
	s_nop 1
	v_permlane32_swap_b32_e32 v28, v30
	v_permlane32_swap_b32_e32 v29, v31
	global_store_dwordx4 v[8:9], v[28:31], off
	s_nop 0
	ds_read_b128 v[32:35], v137 offset:64
	v_mul_f32_e32 v37, v118, v14
	v_mul_f32_e32 v39, v117, v14
	v_mul_f32_e32 v41, v116, v14
	v_mul_f32_e32 v43, v115, v14
	s_waitcnt vmcnt(7)
	v_mov_b32_e32 v28, v150
	v_mov_b32_e32 v29, v151
	v_mov_b32_e32 v30, v152
	v_mov_b32_e32 v31, v153
	s_nop 1
	v_permlane32_swap_b32_e32 v28, v30
	v_permlane32_swap_b32_e32 v29, v31
	s_waitcnt lgkmcnt(0)
	v_mov_b32_e32 v45, v32
	v_mov_b32_e32 v47, v34
	v_lshlrev_b32_e32 v36, 16, v28
	v_and_b32_e32 v38, 0xffff0000, v28
	v_lshlrev_b32_e32 v40, 16, v29
	v_and_b32_e32 v42, 0xffff0000, v29
	v_mul_f32_e32 v28, 0xbfb8aa3b, v36
	v_mul_f32_e32 v29, 0xbfb8aa3b, v38
	v_mul_f32_e32 v32, 0xbfb8aa3b, v40
	v_mul_f32_e32 v34, 0xbfb8aa3b, v42
	v_exp_f32_e32 v28, v28
	v_exp_f32_e32 v29, v29
	v_exp_f32_e32 v32, v32
	v_exp_f32_e32 v34, v34
	v_add_f32_e32 v28, 1.0, v28
	v_add_f32_e32 v29, 1.0, v29
	v_add_f32_e32 v46, 1.0, v32
	v_add_f32_e32 v34, 1.0, v34
	v_rcp_f32_e32 v44, v28
	v_rcp_f32_e32 v32, v29
	v_rcp_f32_e32 v46, v46
	v_rcp_f32_e32 v34, v34
	v_pk_mul_f32 v[28:29], v[44:45], v[36:37]
	v_pk_mul_f32 v[32:33], v[32:33], v[38:39]
	v_pk_mul_f32 v[36:37], v[46:47], v[40:41]
	v_pk_mul_f32 v[34:35], v[34:35], v[42:43]
	v_mul_f32_e32 v28, v28, v29
	v_mul_f32_e32 v29, v32, v33
	v_mul_f32_e32 v32, v36, v37
	v_mul_f32_e32 v33, v34, v35
	v_cvt_pk_bf16_f32 v44, v28, v29
	v_cvt_pk_bf16_f32 v45, v32, v33
	ds_read_b128 v[32:35], v137 offset:96
	v_mov_b32_e32 v15, v30
	v_lshlrev_b32_e32 v28, 16, v15
	v_lshlrev_b32_e32 v38, 16, v31
	v_and_b32_e32 v36, 0xffff0000, v15
	v_and_b32_e32 v40, 0xffff0000, v31
	v_mul_f32_e32 v15, 0xbfb8aa3b, v28
	v_mul_f32_e32 v31, 0xbfb8aa3b, v38
	v_mul_f32_e32 v30, 0xbfb8aa3b, v36
	v_mul_f32_e32 v42, 0xbfb8aa3b, v40
	v_exp_f32_e32 v15, v15
	v_exp_f32_e32 v31, v31
	v_exp_f32_e32 v30, v30
	v_exp_f32_e32 v42, v42
	v_add_f32_e32 v15, 1.0, v15
	v_add_f32_e32 v31, 1.0, v31
	v_add_f32_e32 v43, 1.0, v30
	v_add_f32_e32 v46, 1.0, v42
	v_rcp_f32_e32 v30, v15
	v_rcp_f32_e32 v42, v31
	v_mul_f32_e32 v29, v114, v14
	v_mul_f32_e32 v39, v112, v14
	v_mul_f32_e32 v37, v113, v14
	v_mul_f32_e32 v41, v78, v14
	s_waitcnt lgkmcnt(0)
; __device__ __forceinline__ unsigned pk2(float lo, float hi) { return pg8::cvt_pk_bf16(lo, hi); }
; __device__ __forceinline__ float siluf_(float v) { return v * __builtin_amdgcn_rcpf(1.f + __builtin_amdgcn_exp2f(-LOG2E * v)); }
; __device__ __forceinline__ void attn_unit(int b, int h, int qb, bf16_t* Q, const bf16_t* __restrict__ K, const bf16_t* __restrict__ Vt, const bf16_t* __restrict__ Z, const float* __restrict__ hg, float lam, ...
;     ...
;     for (int d = 0; d < 4; ++d)
; #pragma unroll
;         for (int ip = 0; ip < 2; ++ip) { __builtin_amdgcn_sched_barrier(0);
;             u32x2 w[2];
;             const u32x4 zl = *(const u32x4*)(Z + offw + 32 * d + 16 * ip + 8 * hi_l);
;             const unsigned zsx = hi_l ? zl.x : zl.z, zsy = hi_l ? zl.y : zl.w;
;             const unsigned zrx = __shfl_xor(zsx, 32), zry = __shfl_xor(zsy, 32);
; #pragma unroll
;             for (int k = 0; k < 2; ++k) { const int i = 2 * ip + k, e = 32 * d + 8 * i;
;                 const f32x4 g4 = *(const f32x4*)(hg + e + 4 * hi_l);
;                 const u32x2 z2 = (k == 0) ? (hi_l ? (u32x2){zrx, zry} : (u32x2){zl.x, zl.y}) : (hi_l ? (u32x2){zl.z, zl.w} : (u32x2){zrx, zry});
;                 const float v0 = o[0][d][4 * i] * rs * g4[0] * siluf_(bflo(z2.x)), v1 = o[0][d][4 * i + 1] * rs * g4[1] * siluf_(bfhi(z2.x));
;                 const float v2 = o[0][d][4 * i + 2] * rs * g4[2] * siluf_(bflo(z2.y)), v3 = o[0][d][4 * i + 3] * rs * g4[3] * siluf_(bfhi(z2.y));
;                 w[k] = (u32x2){pk2(v0, v1), pk2(v2, v3)}; }
;             const u32x2 snd = hi_l ? w[0] : w[1];
;             const unsigned rx = __shfl_xor(snd.x, 32), ry = __shfl_xor(snd.y, 32);
;             const u32x4 st = hi_l ? (u32x4){rx, ry, w[1].x, w[1].y} : (u32x4){w[0].x, w[0].y, rx, ry};
;             *(u32x4*)(Q + offw + 32 * d + 16 * ip + 8 * hi_l) = st; }
	v_mov_b32_e32 v31, v32
	v_rcp_f32_e32 v32, v43
	v_mov_b32_e32 v43, v34
	v_rcp_f32_e32 v34, v46
	v_pk_mul_f32 v[28:29], v[30:31], v[28:29]
	v_pk_mul_f32 v[30:31], v[42:43], v[38:39]
	v_mul_f32_e32 v15, v28, v29
	v_mul_f32_e32 v38, v30, v31
	v_pk_mul_f32 v[28:29], v[32:33], v[36:37]
	v_pk_mul_f32 v[30:31], v[34:35], v[40:41]
	v_mul_f32_e32 v28, v28, v29
	v_mul_f32_e32 v29, v30, v31
	v_cvt_pk_bf16_f32 v15, v15, v28
	v_cvt_pk_bf16_f32 v29, v38, v29
	s_nop 0
	v_mov_b32_e32 v31, v29
	v_mov_b32_e32 v30, v15
	v_mov_b32_e32 v28, v44
	v_mov_b32_e32 v29, v45
	s_nop 1
	v_permlane32_swap_b32_e32 v28, v30
	v_permlane32_swap_b32_e32 v29, v31
	global_store_dwordx4 v[8:9], v[28:31], off offset:32
	s_nop 0
	ds_read_b128 v[32:35], v137 offset:128
	v_mul_f32_e32 v37, v77, v14
	v_mul_f32_e32 v39, v76, v14
	v_mul_f32_e32 v41, v75, v14
	v_mul_f32_e32 v43, v74, v14
	s_waitcnt vmcnt(7)
	v_mov_b32_e32 v28, v154
	v_mov_b32_e32 v29, v155
	v_mov_b32_e32 v30, v156
	v_mov_b32_e32 v31, v157
	s_nop 1
	v_permlane32_swap_b32_e32 v28, v30
	v_permlane32_swap_b32_e32 v29, v31
	s_waitcnt lgkmcnt(0)
	v_mov_b32_e32 v45, v32
	v_mov_b32_e32 v47, v34
	v_lshlrev_b32_e32 v36, 16, v28
	v_and_b32_e32 v38, 0xffff0000, v28
	v_lshlrev_b32_e32 v40, 16, v29
	v_and_b32_e32 v42, 0xffff0000, v29
	v_mul_f32_e32 v28, 0xbfb8aa3b, v36
	v_mul_f32_e32 v29, 0xbfb8aa3b, v38
	v_mul_f32_e32 v32, 0xbfb8aa3b, v40
	v_mul_f32_e32 v34, 0xbfb8aa3b, v42
	v_exp_f32_e32 v28, v28
	v_exp_f32_e32 v29, v29
	v_exp_f32_e32 v32, v32
	v_exp_f32_e32 v34, v34
	v_add_f32_e32 v28, 1.0, v28
	v_add_f32_e32 v29, 1.0, v29
	v_add_f32_e32 v46, 1.0, v32
	v_add_f32_e32 v34, 1.0, v34
	v_rcp_f32_e32 v44, v28
	v_rcp_f32_e32 v32, v29
	v_rcp_f32_e32 v46, v46
	v_rcp_f32_e32 v34, v34
	v_pk_mul_f32 v[28:29], v[44:45], v[36:37]
	v_pk_mul_f32 v[32:33], v[32:33], v[38:39]
	v_pk_mul_f32 v[36:37], v[46:47], v[40:41]
	v_pk_mul_f32 v[34:35], v[34:35], v[42:43]
	v_mul_f32_e32 v28, v28, v29
	v_mul_f32_e32 v29, v32, v33
	v_mul_f32_e32 v32, v36, v37
	v_mul_f32_e32 v33, v34, v35
	v_cvt_pk_bf16_f32 v44, v28, v29
	v_cvt_pk_bf16_f32 v45, v32, v33
	ds_read_b128 v[32:35], v137 offset:160
	v_mov_b32_e32 v15, v30
	v_lshlrev_b32_e32 v28, 16, v15
	v_lshlrev_b32_e32 v38, 16, v31
	v_and_b32_e32 v36, 0xffff0000, v15
	v_and_b32_e32 v40, 0xffff0000, v31
	v_mul_f32_e32 v15, 0xbfb8aa3b, v28
	v_mul_f32_e32 v31, 0xbfb8aa3b, v38
	v_mul_f32_e32 v30, 0xbfb8aa3b, v36
	v_mul_f32_e32 v42, 0xbfb8aa3b, v40
	v_exp_f32_e32 v15, v15
	v_exp_f32_e32 v31, v31
	v_exp_f32_e32 v30, v30
	v_exp_f32_e32 v42, v42
	v_add_f32_e32 v15, 1.0, v15
	v_add_f32_e32 v31, 1.0, v31
	v_add_f32_e32 v43, 1.0, v30
	v_add_f32_e32 v46, 1.0, v42
	v_rcp_f32_e32 v30, v15
	v_rcp_f32_e32 v42, v31
	v_mul_f32_e32 v29, v73, v14
	v_mul_f32_e32 v39, v71, v14
	v_mul_f32_e32 v37, v72, v14
	v_mul_f32_e32 v41, v70, v14
	s_waitcnt lgkmcnt(0)
	v_mov_b32_e32 v31, v32
	v_rcp_f32_e32 v32, v43
	v_mov_b32_e32 v43, v34
	v_rcp_f32_e32 v34, v46
	v_pk_mul_f32 v[28:29], v[30:31], v[28:29]
	v_pk_mul_f32 v[30:31], v[42:43], v[38:39]
	v_mul_f32_e32 v15, v28, v29
	v_mul_f32_e32 v38, v30, v31
	v_pk_mul_f32 v[28:29], v[32:33], v[36:37]
	v_pk_mul_f32 v[30:31], v[34:35], v[40:41]
	v_mul_f32_e32 v28, v28, v29
	v_mul_f32_e32 v29, v30, v31
	v_cvt_pk_bf16_f32 v15, v15, v28
	v_cvt_pk_bf16_f32 v29, v38, v29
	s_nop 0
	v_mov_b32_e32 v31, v29
	v_mov_b32_e32 v30, v15
	v_mov_b32_e32 v28, v44
	v_mov_b32_e32 v29, v45
	s_nop 1
	v_permlane32_swap_b32_e32 v28, v30
	v_permlane32_swap_b32_e32 v29, v31
	global_store_dwordx4 v[8:9], v[28:31], off offset:64
	s_nop 0
	ds_read_b128 v[32:35], v137 offset:192
	v_mul_f32_e32 v37, v69, v14
	v_mul_f32_e32 v39, v68, v14
	v_mul_f32_e32 v41, v67, v14
	v_mul_f32_e32 v43, v66, v14
	s_waitcnt vmcnt(7)
	v_mov_b32_e32 v28, v158
	v_mov_b32_e32 v29, v159
	v_mov_b32_e32 v30, v160
	v_mov_b32_e32 v31, v161
	s_nop 1
	v_permlane32_swap_b32_e32 v28, v30
	v_permlane32_swap_b32_e32 v29, v31
	s_waitcnt lgkmcnt(0)
	v_mov_b32_e32 v45, v32
	v_mov_b32_e32 v47, v34
	v_lshlrev_b32_e32 v36, 16, v28
	v_and_b32_e32 v38, 0xffff0000, v28
	v_lshlrev_b32_e32 v40, 16, v29
	v_and_b32_e32 v42, 0xffff0000, v29
	v_mul_f32_e32 v28, 0xbfb8aa3b, v36
	v_mul_f32_e32 v29, 0xbfb8aa3b, v38
	v_mul_f32_e32 v32, 0xbfb8aa3b, v40
	v_mul_f32_e32 v34, 0xbfb8aa3b, v42
	v_exp_f32_e32 v28, v28
	v_exp_f32_e32 v29, v29
	v_exp_f32_e32 v32, v32
	v_exp_f32_e32 v34, v34
	v_add_f32_e32 v28, 1.0, v28
	v_add_f32_e32 v29, 1.0, v29
	v_add_f32_e32 v46, 1.0, v32
	v_add_f32_e32 v34, 1.0, v34
	v_rcp_f32_e32 v44, v28
	v_rcp_f32_e32 v32, v29
	v_rcp_f32_e32 v46, v46
	v_rcp_f32_e32 v34, v34
	v_pk_mul_f32 v[28:29], v[44:45], v[36:37]
	v_pk_mul_f32 v[32:33], v[32:33], v[38:39]
	v_pk_mul_f32 v[36:37], v[46:47], v[40:41]
	v_pk_mul_f32 v[34:35], v[34:35], v[42:43]
	v_mul_f32_e32 v28, v28, v29
	v_mul_f32_e32 v29, v32, v33
	v_mul_f32_e32 v32, v36, v37
	v_mul_f32_e32 v33, v34, v35
	v_cvt_pk_bf16_f32 v44, v28, v29
	v_cvt_pk_bf16_f32 v45, v32, v33
	ds_read_b128 v[32:35], v137 offset:224
	v_mov_b32_e32 v15, v30
	v_lshlrev_b32_e32 v28, 16, v15
	v_lshlrev_b32_e32 v38, 16, v31
	v_and_b32_e32 v36, 0xffff0000, v15
	v_and_b32_e32 v40, 0xffff0000, v31
	v_mul_f32_e32 v15, 0xbfb8aa3b, v28
	v_mul_f32_e32 v31, 0xbfb8aa3b, v38
	v_mul_f32_e32 v30, 0xbfb8aa3b, v36
	v_mul_f32_e32 v42, 0xbfb8aa3b, v40
	v_exp_f32_e32 v15, v15
	v_exp_f32_e32 v31, v31
	v_exp_f32_e32 v30, v30
	v_exp_f32_e32 v42, v42
	v_add_f32_e32 v15, 1.0, v15
	v_add_f32_e32 v31, 1.0, v31
	v_add_f32_e32 v43, 1.0, v30
	v_add_f32_e32 v46, 1.0, v42
	v_rcp_f32_e32 v30, v15
	v_rcp_f32_e32 v42, v31
	v_mul_f32_e32 v29, v65, v14
	v_mul_f32_e32 v39, v61, v14
	v_mul_f32_e32 v37, v64, v14
	v_mul_f32_e32 v41, v60, v14
	s_waitcnt lgkmcnt(0)
; __device__ __forceinline__ unsigned pk2(float lo, float hi) { return pg8::cvt_pk_bf16(lo, hi); }
; __device__ __forceinline__ float siluf_(float v) { return v * __builtin_amdgcn_rcpf(1.f + __builtin_amdgcn_exp2f(-LOG2E * v)); }
; __device__ __forceinline__ void attn_unit(int b, int h, int qb, bf16_t* Q, const bf16_t* __restrict__ K, const bf16_t* __restrict__ Vt, const bf16_t* __restrict__ Z, const float* __restrict__ hg, float lam, ...
;     ...
; #pragma unroll
;     for (int d = 0; d < 4; ++d)
; #pragma unroll
;         for (int ip = 0; ip < 2; ++ip) { __builtin_amdgcn_sched_barrier(0);
;             u32x2 w[2];
;             const u32x4 zl = *(const u32x4*)(Z + offw + 32 * d + 16 * ip + 8 * hi_l);
;             const unsigned zsx = hi_l ? zl.x : zl.z, zsy = hi_l ? zl.y : zl.w;
;             const unsigned zrx = __shfl_xor(zsx, 32), zry = __shfl_xor(zsy, 32);
; #pragma unroll
;             for (int k = 0; k < 2; ++k) { const int i = 2 * ip + k, e = 32 * d + 8 * i;
;                 const f32x4 g4 = *(const f32x4*)(hg + e + 4 * hi_l);
;                 const u32x2 z2 = (k == 0) ? (hi_l ? (u32x2){zrx, zry} : (u32x2){zl.x, zl.y}) : (hi_l ? (u32x2){zl.z, zl.w} : (u32x2){zrx, zry});
;                 const float v0 = o[0][d][4 * i] * rs * g4[0] * siluf_(bflo(z2.x)), v1 = o[0][d][4 * i + 1] * rs * g4[1] * siluf_(bfhi(z2.x));
;                 const float v2 = o[0][d][4 * i + 2] * rs * g4[2] * siluf_(bflo(z2.y)), v3 = o[0][d][4 * i + 3] * rs * g4[3] * siluf_(bfhi(z2.y));
;                 w[k] = (u32x2){pk2(v0, v1), pk2(v2, v3)}; }
;             const u32x2 snd = hi_l ? w[0] : w[1];
;             const unsigned rx = __shfl_xor(snd.x, 32), ry = __shfl_xor(snd.y, 32);
;             const u32x4 st = hi_l ? (u32x4){rx, ry, w[1].x, w[1].y} : (u32x4){w[0].x, w[0].y, rx, ry};
;             *(u32x4*)(Q + offw + 32 * d + 16 * ip + 8 * hi_l) = st; }
	v_mov_b32_e32 v31, v32
	v_rcp_f32_e32 v32, v43
	v_mov_b32_e32 v43, v34
	v_rcp_f32_e32 v34, v46
	v_pk_mul_f32 v[28:29], v[30:31], v[28:29]
	v_pk_mul_f32 v[30:31], v[42:43], v[38:39]
	v_mul_f32_e32 v15, v28, v29
	v_mul_f32_e32 v38, v30, v31
	v_pk_mul_f32 v[28:29], v[32:33], v[36:37]
	v_pk_mul_f32 v[30:31], v[34:35], v[40:41]
	v_mul_f32_e32 v28, v28, v29
	v_mul_f32_e32 v29, v30, v31
	v_cvt_pk_bf16_f32 v15, v15, v28
	v_cvt_pk_bf16_f32 v29, v38, v29
	s_nop 0
	v_mov_b32_e32 v31, v29
	v_mov_b32_e32 v30, v15
	v_mov_b32_e32 v28, v44
	v_mov_b32_e32 v29, v45
	s_nop 1
	v_permlane32_swap_b32_e32 v28, v30
	v_permlane32_swap_b32_e32 v29, v31
	global_store_dwordx4 v[8:9], v[28:31], off offset:96
	s_nop 0
	ds_read_b128 v[32:35], v137 offset:256
	v_mul_f32_e32 v41, v57, v14
	v_mul_f32_e32 v37, v59, v14
	v_mul_f32_e32 v39, v58, v14
	v_mul_f32_e32 v43, v56, v14
	s_waitcnt vmcnt(7)
	v_mov_b32_e32 v28, v162
	v_mov_b32_e32 v29, v163
	v_mov_b32_e32 v30, v164
	v_mov_b32_e32 v31, v165
	s_nop 1
	v_permlane32_swap_b32_e32 v28, v30
	v_permlane32_swap_b32_e32 v29, v31
	s_waitcnt lgkmcnt(0)
	v_mov_b32_e32 v45, v32
	v_mov_b32_e32 v47, v34
	v_lshlrev_b32_e32 v36, 16, v28
	v_and_b32_e32 v38, 0xffff0000, v28
	v_lshlrev_b32_e32 v40, 16, v29
	v_and_b32_e32 v42, 0xffff0000, v29
	v_mul_f32_e32 v28, 0xbfb8aa3b, v36
	v_mul_f32_e32 v29, 0xbfb8aa3b, v38
	v_mul_f32_e32 v32, 0xbfb8aa3b, v40
	v_mul_f32_e32 v34, 0xbfb8aa3b, v42
	v_exp_f32_e32 v28, v28
	v_exp_f32_e32 v29, v29
	v_exp_f32_e32 v32, v32
	v_exp_f32_e32 v34, v34
	v_add_f32_e32 v28, 1.0, v28
	v_add_f32_e32 v29, 1.0, v29
	v_add_f32_e32 v46, 1.0, v32
	v_add_f32_e32 v34, 1.0, v34
	v_rcp_f32_e32 v44, v28
	v_rcp_f32_e32 v32, v29
	v_rcp_f32_e32 v46, v46
	v_rcp_f32_e32 v34, v34
	v_pk_mul_f32 v[28:29], v[44:45], v[36:37]
	v_pk_mul_f32 v[32:33], v[32:33], v[38:39]
	v_pk_mul_f32 v[36:37], v[46:47], v[40:41]
	v_pk_mul_f32 v[34:35], v[34:35], v[42:43]
	v_mul_f32_e32 v28, v28, v29
	v_mul_f32_e32 v29, v32, v33
	v_mul_f32_e32 v32, v36, v37
	v_mul_f32_e32 v33, v34, v35
	v_cvt_pk_bf16_f32 v44, v28, v29
	v_cvt_pk_bf16_f32 v45, v32, v33
	ds_read_b128 v[32:35], v137 offset:288
	v_mov_b32_e32 v15, v30
	v_lshlrev_b32_e32 v28, 16, v15
	v_lshlrev_b32_e32 v38, 16, v31
	v_and_b32_e32 v36, 0xffff0000, v15
	v_and_b32_e32 v40, 0xffff0000, v31
	v_mul_f32_e32 v15, 0xbfb8aa3b, v28
	v_mul_f32_e32 v31, 0xbfb8aa3b, v38
	v_mul_f32_e32 v30, 0xbfb8aa3b, v36
	v_mul_f32_e32 v42, 0xbfb8aa3b, v40
	v_exp_f32_e32 v15, v15
	v_exp_f32_e32 v31, v31
	v_exp_f32_e32 v30, v30
	v_exp_f32_e32 v42, v42
	v_add_f32_e32 v15, 1.0, v15
	v_add_f32_e32 v31, 1.0, v31
	v_add_f32_e32 v43, 1.0, v30
	v_add_f32_e32 v46, 1.0, v42
	v_rcp_f32_e32 v30, v15
	v_rcp_f32_e32 v42, v31
	v_mul_f32_e32 v29, v55, v14
	v_mul_f32_e32 v39, v53, v14
	v_mul_f32_e32 v37, v54, v14
	v_mul_f32_e32 v41, v52, v14
	s_waitcnt lgkmcnt(0)
	v_mov_b32_e32 v31, v32
	v_rcp_f32_e32 v32, v43
	v_mov_b32_e32 v43, v34
	v_rcp_f32_e32 v34, v46
	v_pk_mul_f32 v[28:29], v[30:31], v[28:29]
	v_pk_mul_f32 v[30:31], v[42:43], v[38:39]
	v_mul_f32_e32 v15, v28, v29
	v_mul_f32_e32 v38, v30, v31
	v_pk_mul_f32 v[28:29], v[32:33], v[36:37]
	v_pk_mul_f32 v[30:31], v[34:35], v[40:41]
	v_mul_f32_e32 v28, v28, v29
	v_mul_f32_e32 v29, v30, v31
	v_cvt_pk_bf16_f32 v15, v15, v28
	v_cvt_pk_bf16_f32 v29, v38, v29
	s_nop 0
	v_mov_b32_e32 v31, v29
	v_mov_b32_e32 v30, v15
	v_mov_b32_e32 v28, v44
	v_mov_b32_e32 v29, v45
	s_nop 1
	v_permlane32_swap_b32_e32 v28, v30
	v_permlane32_swap_b32_e32 v29, v31
	global_store_dwordx4 v[8:9], v[28:31], off offset:128
	s_nop 0
	ds_read_b128 v[32:35], v137 offset:320
	v_mul_f32_e32 v42, v48, v14
	v_mul_f32_e32 v40, v49, v14
	v_mul_f32_e32 v36, v51, v14
	v_mul_f32_e32 v38, v50, v14
	v_mul_f32_e32 v26, v26, v14
	v_mul_f32_e32 v24, v24, v14
	s_waitcnt vmcnt(7)
	v_mov_b32_e32 v28, v166
	v_mov_b32_e32 v29, v167
	v_mov_b32_e32 v30, v168
	v_mov_b32_e32 v31, v169
	s_nop 1
	v_permlane32_swap_b32_e32 v28, v30
	v_permlane32_swap_b32_e32 v29, v31
	s_waitcnt lgkmcnt(0)
	v_mov_b32_e32 v44, v33
	v_mov_b32_e32 v46, v35
	v_lshlrev_b32_e32 v37, 16, v28
	v_and_b32_e32 v39, 0xffff0000, v28
	v_lshlrev_b32_e32 v41, 16, v29
	v_and_b32_e32 v43, 0xffff0000, v29
	v_mul_f32_e32 v28, 0xbfb8aa3b, v37
	v_mul_f32_e32 v29, 0xbfb8aa3b, v39
	v_mul_f32_e32 v33, 0xbfb8aa3b, v41
	v_mul_f32_e32 v35, 0xbfb8aa3b, v43
	v_exp_f32_e32 v28, v28
	v_exp_f32_e32 v29, v29
	v_exp_f32_e32 v33, v33
	v_exp_f32_e32 v35, v35
	v_add_f32_e32 v28, 1.0, v28
	v_add_f32_e32 v29, 1.0, v29
	v_add_f32_e32 v47, 1.0, v33
	v_add_f32_e32 v49, 1.0, v35
	v_rcp_f32_e32 v33, v28
	v_rcp_f32_e32 v45, v29
	v_rcp_f32_e32 v35, v47
	v_rcp_f32_e32 v47, v49
	v_pk_mul_f32 v[28:29], v[32:33], v[36:37]
	v_pk_mul_f32 v[32:33], v[44:45], v[38:39]
	v_pk_mul_f32 v[34:35], v[34:35], v[40:41]
	v_pk_mul_f32 v[36:37], v[46:47], v[42:43]
	v_mul_f32_e32 v28, v28, v29
	v_mul_f32_e32 v29, v32, v33
	v_mul_f32_e32 v32, v34, v35
	v_mul_f32_e32 v33, v36, v37
	v_cvt_pk_bf16_f32 v44, v28, v29
	v_cvt_pk_bf16_f32 v45, v32, v33
	ds_read_b128 v[32:35], v137 offset:352
	v_mul_f32_e32 v36, v25, v14
	v_mov_b32_e32 v25, v31
	v_mov_b32_e32 v15, v30
	v_mul_f32_e32 v28, v27, v14
	v_lshlrev_b32_e32 v29, 16, v15
	v_and_b32_e32 v27, 0xffff0000, v15
	v_lshlrev_b32_e32 v37, 16, v25
	v_and_b32_e32 v25, 0xffff0000, v25
	v_mul_f32_e32 v15, 0xbfb8aa3b, v29
	v_mul_f32_e32 v30, 0xbfb8aa3b, v27
	v_mul_f32_e32 v38, 0xbfb8aa3b, v25
	v_mul_f32_e32 v31, 0xbfb8aa3b, v37
	v_exp_f32_e32 v15, v15
	v_exp_f32_e32 v30, v30
	v_exp_f32_e32 v38, v38
	v_exp_f32_e32 v31, v31
	v_add_f32_e32 v15, 1.0, v15
	v_add_f32_e32 v30, 1.0, v30
	v_add_f32_e32 v38, 1.0, v38
	v_add_f32_e32 v40, 1.0, v31
	v_rcp_f32_e32 v31, v15
	v_rcp_f32_e32 v39, v30
	v_rcp_f32_e32 v43, v38
	v_rcp_f32_e32 v41, v40
	s_waitcnt lgkmcnt(0)
; __device__ __forceinline__ unsigned pk2(float lo, float hi) { return pg8::cvt_pk_bf16(lo, hi); }
; __device__ __forceinline__ float siluf_(float v) { return v * __builtin_amdgcn_rcpf(1.f + __builtin_amdgcn_exp2f(-LOG2E * v)); }
; __device__ __forceinline__ void attn_unit(int b, int h, int qb, bf16_t* Q, const bf16_t* __restrict__ K, const bf16_t* __restrict__ Vt, const bf16_t* __restrict__ Z, const float* __restrict__ hg, float lam, ...
;     ...
; #pragma unroll
;     for (int d = 0; d < 4; ++d)
; #pragma unroll
;         for (int ip = 0; ip < 2; ++ip) { __builtin_amdgcn_sched_barrier(0);
;             u32x2 w[2];
;             const u32x4 zl = *(const u32x4*)(Z + offw + 32 * d + 16 * ip + 8 * hi_l);
;             const unsigned zsx = hi_l ? zl.x : zl.z, zsy = hi_l ? zl.y : zl.w;
;             const unsigned zrx = __shfl_xor(zsx, 32), zry = __shfl_xor(zsy, 32);
; #pragma unroll
;             for (int k = 0; k < 2; ++k) { const int i = 2 * ip + k, e = 32 * d + 8 * i;
;                 const f32x4 g4 = *(const f32x4*)(hg + e + 4 * hi_l);
;                 const u32x2 z2 = (k == 0) ? (hi_l ? (u32x2){zrx, zry} : (u32x2){zl.x, zl.y}) : (hi_l ? (u32x2){zl.z, zl.w} : (u32x2){zrx, zry});
;                 const float v0 = o[0][d][4 * i] * rs * g4[0] * siluf_(bflo(z2.x)), v1 = o[0][d][4 * i + 1] * rs * g4[1] * siluf_(bfhi(z2.x));
;                 const float v2 = o[0][d][4 * i + 2] * rs * g4[2] * siluf_(bflo(z2.y)), v3 = o[0][d][4 * i + 3] * rs * g4[3] * siluf_(bfhi(z2.y));
;                 w[k] = (u32x2){pk2(v0, v1), pk2(v2, v3)}; }
;             const u32x2 snd = hi_l ? w[0] : w[1];
;             const unsigned rx = __shfl_xor(snd.x, 32), ry = __shfl_xor(snd.y, 32);
;             const u32x4 st = hi_l ? (u32x4){rx, ry, w[1].x, w[1].y} : (u32x4){w[0].x, w[0].y, rx, ry};
;             *(u32x4*)(Q + offw + 32 * d + 16 * ip + 8 * hi_l) = st; }
	v_mov_b32_e32 v30, v32
	v_mov_b32_e32 v38, v33
	v_mov_b32_e32 v42, v35
	v_mov_b32_e32 v40, v34
	v_pk_mul_f32 v[28:29], v[30:31], v[28:29]
	v_pk_mul_f32 v[26:27], v[38:39], v[26:27]
	v_pk_mul_f32 v[24:25], v[42:43], v[24:25]
	v_pk_mul_f32 v[30:31], v[40:41], v[36:37]
	v_mul_f32_e32 v15, v28, v29
	v_mul_f32_e32 v26, v26, v27
	v_mul_f32_e32 v24, v24, v25
	v_mul_f32_e32 v27, v30, v31
	v_cvt_pk_bf16_f32 v15, v15, v26
	v_cvt_pk_bf16_f32 v25, v27, v24
	s_nop 0
	v_mov_b32_e32 v27, v25
	v_mov_b32_e32 v26, v15
	v_mov_b32_e32 v24, v44
	v_mov_b32_e32 v25, v45
	s_nop 1
	v_permlane32_swap_b32_e32 v24, v26
	v_permlane32_swap_b32_e32 v25, v27
	global_store_dwordx4 v[8:9], v[24:27], off offset:160
	s_nop 0
	ds_read_b128 v[28:31], v137 offset:384
	v_mul_f32_e32 v34, v21, v14
	v_mul_f32_e32 v32, v23, v14
	v_mul_f32_e32 v22, v22, v14
	v_mul_f32_e32 v20, v20, v14
	v_mul_f32_e32 v18, v18, v14
	v_mul_f32_e32 v16, v16, v14
	s_waitcnt vmcnt(7)
	v_mov_b32_e32 v24, v170
	v_mov_b32_e32 v25, v171
	v_mov_b32_e32 v26, v172
	v_mov_b32_e32 v27, v173
	s_nop 1
	v_permlane32_swap_b32_e32 v24, v26
	v_permlane32_swap_b32_e32 v25, v27
	s_waitcnt lgkmcnt(0)
	v_mov_b32_e32 v36, v29
	v_mov_b32_e32 v38, v31
	v_mov_b32_e32 v21, v25
	v_mov_b32_e32 v23, v24
	v_lshlrev_b32_e32 v29, 16, v23
	v_and_b32_e32 v37, 0xffff0000, v23
	v_lshlrev_b32_e32 v31, 16, v21
	v_and_b32_e32 v39, 0xffff0000, v21
	v_mul_f32_e32 v21, 0xbfb8aa3b, v29
	v_mul_f32_e32 v23, 0xbfb8aa3b, v37
	v_mul_f32_e32 v24, 0xbfb8aa3b, v31
	v_mul_f32_e32 v25, 0xbfb8aa3b, v39
	v_exp_f32_e32 v21, v21
	v_exp_f32_e32 v23, v23
	v_exp_f32_e32 v24, v24
	v_exp_f32_e32 v25, v25
	v_add_f32_e32 v21, 1.0, v21
	v_add_f32_e32 v23, 1.0, v23
	v_add_f32_e32 v24, 1.0, v24
	v_add_f32_e32 v25, 1.0, v25
	v_rcp_f32_e32 v33, v21
	v_rcp_f32_e32 v23, v23
	v_rcp_f32_e32 v35, v24
	v_rcp_f32_e32 v21, v25
	v_pk_mul_f32 v[24:25], v[32:33], v[28:29]
	v_pk_mul_f32 v[22:23], v[22:23], v[36:37]
	v_pk_mul_f32 v[28:29], v[34:35], v[30:31]
	v_pk_mul_f32 v[20:21], v[20:21], v[38:39]
	v_mul_f32_e32 v22, v22, v23
	v_mul_f32_e32 v23, v28, v29
	v_mul_f32_e32 v20, v20, v21
	v_mul_f32_e32 v24, v24, v25
	v_cvt_pk_bf16_f32 v36, v24, v22
	v_cvt_pk_bf16_f32 v37, v23, v20
	ds_read_b128 v[20:23], v137 offset:416
	v_mul_f32_e32 v28, v17, v14
	v_mov_b32_e32 v17, v27
	v_mov_b32_e32 v15, v26
	v_lshlrev_b32_e32 v27, 16, v15
	v_and_b32_e32 v31, 0xffff0000, v15
	v_and_b32_e32 v35, 0xffff0000, v17
	v_lshlrev_b32_e32 v33, 16, v17
	v_mul_f32_e32 v15, 0xbfb8aa3b, v27
	v_mul_f32_e32 v17, 0xbfb8aa3b, v31
	v_mul_f32_e32 v25, 0xbfb8aa3b, v35
	v_mul_f32_e32 v24, v19, v14
	v_mul_f32_e32 v19, 0xbfb8aa3b, v33
	v_exp_f32_e32 v15, v15
	v_exp_f32_e32 v17, v17
	v_exp_f32_e32 v25, v25
	v_exp_f32_e32 v19, v19
	v_add_f32_e32 v15, 1.0, v15
	v_add_f32_e32 v17, 1.0, v17
	v_add_f32_e32 v30, 1.0, v25
	v_add_f32_e32 v26, 1.0, v19
	v_rcp_f32_e32 v25, v15
	v_rcp_f32_e32 v19, v17
	v_rcp_f32_e32 v17, v30
	v_rcp_f32_e32 v29, v26
	s_waitcnt lgkmcnt(0)
	v_mov_b32_e32 v26, v20
	v_mov_b32_e32 v30, v21
	v_mov_b32_e32 v34, v23
	v_mov_b32_e32 v32, v22
	v_pk_mul_f32 v[20:21], v[24:25], v[26:27]
	v_pk_mul_f32 v[18:19], v[18:19], v[30:31]
	v_pk_mul_f32 v[16:17], v[16:17], v[34:35]
	v_pk_mul_f32 v[22:23], v[28:29], v[32:33]
	v_mul_f32_e32 v15, v20, v21
	v_mul_f32_e32 v18, v18, v19
	v_mul_f32_e32 v16, v16, v17
	v_mul_f32_e32 v19, v22, v23
	v_cvt_pk_bf16_f32 v15, v15, v18
	v_cvt_pk_bf16_f32 v17, v19, v16
	s_nop 0
	v_mov_b32_e32 v19, v17
	v_mov_b32_e32 v18, v15
	v_mov_b32_e32 v16, v36
	v_mov_b32_e32 v17, v37
	s_nop 1
	v_permlane32_swap_b32_e32 v16, v18
	v_permlane32_swap_b32_e32 v17, v19
	global_store_dwordx4 v[8:9], v[16:19], off offset:192
	s_nop 0
	ds_read_b128 v[20:23], v137 offset:448
	v_mul_f32_e32 v12, v7, v14
	v_mul_f32_e32 v24, v5, v14
	v_mul_f32_e32 v6, v6, v14
	v_mul_f32_e32 v4, v4, v14
	v_mul_f32_e32 v2, v2, v14
	v_mul_f32_e32 v0, v0, v14
	s_mov_b64 s[8:9], 0
	s_waitcnt vmcnt(7)
	v_mov_b32_e32 v16, v174
	v_mov_b32_e32 v17, v175
	v_mov_b32_e32 v18, v176
	v_mov_b32_e32 v19, v177
	s_nop 1
	v_permlane32_swap_b32_e32 v16, v18
	v_permlane32_swap_b32_e32 v17, v19
	s_waitcnt lgkmcnt(0)
	v_mov_b32_e32 v26, v21
	v_mov_b32_e32 v28, v23
	v_mov_b32_e32 v5, v17
	v_mov_b32_e32 v7, v16
	v_lshlrev_b32_e32 v21, 16, v7
	v_and_b32_e32 v27, 0xffff0000, v7
	v_lshlrev_b32_e32 v23, 16, v5
	v_and_b32_e32 v29, 0xffff0000, v5
	v_mul_f32_e32 v5, 0xbfb8aa3b, v21
	v_mul_f32_e32 v7, 0xbfb8aa3b, v27
	v_mul_f32_e32 v13, 0xbfb8aa3b, v23
	v_mul_f32_e32 v16, 0xbfb8aa3b, v29
	v_exp_f32_e32 v5, v5
	v_exp_f32_e32 v7, v7
	v_exp_f32_e32 v13, v13
	v_exp_f32_e32 v16, v16
	v_add_f32_e32 v5, 1.0, v5
	v_add_f32_e32 v7, 1.0, v7
	v_add_f32_e32 v17, 1.0, v13
	v_add_f32_e32 v16, 1.0, v16
	v_rcp_f32_e32 v13, v5
	v_rcp_f32_e32 v7, v7
	v_rcp_f32_e32 v25, v17
	v_rcp_f32_e32 v5, v16
	v_pk_mul_f32 v[12:13], v[12:13], v[20:21]
	v_pk_mul_f32 v[6:7], v[6:7], v[26:27]
	v_pk_mul_f32 v[16:17], v[24:25], v[22:23]
	v_pk_mul_f32 v[4:5], v[4:5], v[28:29]
	v_mul_f32_e32 v6, v6, v7
	v_mul_f32_e32 v7, v16, v17
	v_mul_f32_e32 v4, v4, v5
	v_mul_f32_e32 v12, v12, v13
	v_cvt_pk_bf16_f32 v22, v12, v6
	v_cvt_pk_bf16_f32 v23, v7, v4
	ds_read_b128 v[4:7], v137 offset:480
	v_mul_f32_e32 v10, v3, v14
	v_mul_f32_e32 v12, v1, v14
	v_mov_b32_e32 v1, v19
	v_mov_b32_e32 v3, v18
	v_lshlrev_b32_e32 v15, 16, v3
	v_and_b32_e32 v17, 0xffff0000, v3
	v_lshlrev_b32_e32 v19, 16, v1
	v_and_b32_e32 v21, 0xffff0000, v1
	v_mul_f32_e32 v1, 0xbfb8aa3b, v15
	v_mul_f32_e32 v3, 0xbfb8aa3b, v17
	v_mul_f32_e32 v11, 0xbfb8aa3b, v19
	v_mul_f32_e32 v13, 0xbfb8aa3b, v21
	v_exp_f32_e32 v1, v1
	v_exp_f32_e32 v3, v3
	v_exp_f32_e32 v11, v11
	v_exp_f32_e32 v13, v13
	v_add_f32_e32 v1, 1.0, v1
	v_add_f32_e32 v14, 1.0, v3
	v_add_f32_e32 v16, 1.0, v11
	v_add_f32_e32 v13, 1.0, v13
	v_rcp_f32_e32 v3, v1
	v_rcp_f32_e32 v11, v14
	v_rcp_f32_e32 v1, v16
	v_rcp_f32_e32 v13, v13
	s_waitcnt lgkmcnt(0)
	v_mov_b32_e32 v14, v4
	v_mov_b32_e32 v16, v5
	v_mov_b32_e32 v18, v6
	v_mov_b32_e32 v20, v7
	v_pk_mul_f32 v[2:3], v[2:3], v[14:15]
	v_pk_mul_f32 v[4:5], v[10:11], v[16:17]
	v_pk_mul_f32 v[0:1], v[0:1], v[18:19]
	v_pk_mul_f32 v[6:7], v[12:13], v[20:21]
	v_mul_f32_e32 v2, v2, v3
	v_mul_f32_e32 v3, v4, v5
	v_mul_f32_e32 v0, v0, v1
	v_mul_f32_e32 v1, v6, v7
	v_cvt_pk_bf16_f32 v2, v2, v3
	v_cvt_pk_bf16_f32 v1, v0, v1
	s_nop 0
	v_mov_b32_e32 v3, v1
	v_mov_b32_e32 v0, v22
	v_mov_b32_e32 v1, v23
	s_nop 1
	v_permlane32_swap_b32_e32 v0, v2
	v_permlane32_swap_b32_e32 v1, v3
	global_store_dwordx4 v[8:9], v[0:3], off offset:224
